# q-proj/FFN-up GEMM: row rstd prefetched before each unit K-loop instead of loaded with an exposed wait at the epilogue start
# baseline (speedup 1.0000x reference)
;     __device__ __forceinline__ void operator()(const f32x4 (&acc)[2][2][4][2], const Unit& u, int wr, int wc, int fr_, int fq_) const {
;     ...
;         const int col0 = u.pn * BM + wc * 32 + 8 * fq, rowb = u.pm * BM + wr * 64 + fr;
;         float rs[2][4];
; #pragma unroll
;         for (int ai = 0; ai < 2; ++ai)
; #pragma unroll
;             for (int m = 0; m < 4; ++m) rs[ai][m] = rstd[rowb + ai * HALF + m * 16];
; template <class Epi, class Sched, bool ALIGN_EPI = false, bool SP2 = false>
; __device__ __forceinline__ void gemm_phase(PG8_LAS unsigned char* lds, const Gemm g, const Sched& S, const Epi& E) {
;     ...
; #pragma unroll
;         for (int a = 0; a < 2; ++a)
; #pragma unroll
;             for (int b = 0; b < 2; ++b)
; #pragma unroll
;                 for (int m = 0; m < 4; ++m)
; #pragma unroll
;                     for (int n = 0; n < 2; ++n) acc[a][b][m][n] = (f32x4){0.f, 0.f, 0.f, 0.f};
.LBB0_2034:
	s_ashr_i32 s27, s26, 31
	s_lshl_b64 s[28:29], s[26:27], 19
	s_add_u32 s28, s44, s28
	s_addc_u32 s29, s45, s29
	s_and_b64 s[30:31], s[0:1], exec
	s_cselect_b32 s5, s29, s37
	s_cselect_b32 s27, s28, s36
	s_ashr_i32 s25, s24, 31
	s_lshl_b64 s[30:31], s[24:25], 19
	s_add_u32 s30, s9, s30
	s_addc_u32 s31, s43, s31
	s_and_b64 s[40:41], s[0:1], exec
	s_cselect_b32 s25, s31, s39
	s_cselect_b32 s35, s30, s38
	s_add_u32 s36, s36, 0x40080
	s_addc_u32 s37, s37, 0
	s_add_u32 s65, s38, 0x100
	v_mov_b32_e32 v0, 0
	s_addc_u32 s66, s39, 0
	s_mov_b32 s67, -2
	v_mov_b32_e32 v1, v0
	v_mov_b32_e32 v2, v0
	v_mov_b32_e32 v3, v0
	v_mov_b32_e32 v4, v0
	v_mov_b32_e32 v5, v0
	v_mov_b32_e32 v6, v0
	v_mov_b32_e32 v7, v0
	v_mov_b32_e32 v16, v0
	v_mov_b32_e32 v17, v0
	v_mov_b32_e32 v18, v0
	v_mov_b32_e32 v19, v0
	v_mov_b32_e32 v20, v0
	v_mov_b32_e32 v21, v0
	v_mov_b32_e32 v22, v0
	v_mov_b32_e32 v23, v0
	v_mov_b32_e32 v32, v0
	v_mov_b32_e32 v33, v0
	v_mov_b32_e32 v34, v0
	v_mov_b32_e32 v35, v0
	v_mov_b32_e32 v36, v0
	v_mov_b32_e32 v37, v0
	v_mov_b32_e32 v38, v0
	v_mov_b32_e32 v39, v0
	v_mov_b32_e32 v48, v0
	v_mov_b32_e32 v49, v0
	v_mov_b32_e32 v50, v0
	v_mov_b32_e32 v51, v0
	v_mov_b32_e32 v52, v0
	v_mov_b32_e32 v53, v0
	v_mov_b32_e32 v54, v0
	v_mov_b32_e32 v55, v0
	v_mov_b32_e32 v8, v0
	v_mov_b32_e32 v9, v0
	v_mov_b32_e32 v10, v0
	v_mov_b32_e32 v11, v0
	v_mov_b32_e32 v12, v0
	v_mov_b32_e32 v13, v0
	v_mov_b32_e32 v14, v0
	v_mov_b32_e32 v15, v0
	v_mov_b32_e32 v24, v0
	v_mov_b32_e32 v25, v0
	v_mov_b32_e32 v26, v0
	v_mov_b32_e32 v27, v0
	v_mov_b32_e32 v28, v0
	v_mov_b32_e32 v29, v0
	v_mov_b32_e32 v30, v0
	v_mov_b32_e32 v31, v0
	v_mov_b32_e32 v40, v0
	v_mov_b32_e32 v41, v0
	v_mov_b32_e32 v42, v0
	v_mov_b32_e32 v43, v0
	v_mov_b32_e32 v44, v0
	v_mov_b32_e32 v45, v0
	v_mov_b32_e32 v46, v0
	v_mov_b32_e32 v47, v0
	v_mov_b32_e32 v56, v0
	v_mov_b32_e32 v57, v0
	v_mov_b32_e32 v58, v0
	v_mov_b32_e32 v59, v0
	v_mov_b32_e32 v60, v0
	v_mov_b32_e32 v61, v0
	v_mov_b32_e32 v62, v0
	v_mov_b32_e32 v63, v0
	v_mov_b32_e32 v64, v0
	v_mov_b32_e32 v65, v0
	v_mov_b32_e32 v66, v0
	v_mov_b32_e32 v67, v0
	v_mov_b32_e32 v68, v0
	v_mov_b32_e32 v69, v0
	v_mov_b32_e32 v70, v0
	v_mov_b32_e32 v71, v0
	v_mov_b32_e32 v80, v0
	v_mov_b32_e32 v81, v0
	v_mov_b32_e32 v82, v0
	v_mov_b32_e32 v83, v0
	v_mov_b32_e32 v84, v0
	v_mov_b32_e32 v85, v0
	v_mov_b32_e32 v86, v0
	v_mov_b32_e32 v87, v0
	v_mov_b32_e32 v96, v0
	v_mov_b32_e32 v97, v0
	v_mov_b32_e32 v98, v0
	v_mov_b32_e32 v99, v0
	v_mov_b32_e32 v100, v0
	v_mov_b32_e32 v101, v0
	v_mov_b32_e32 v102, v0
	v_mov_b32_e32 v103, v0
	v_mov_b32_e32 v112, v0
	v_mov_b32_e32 v113, v0
	v_mov_b32_e32 v114, v0
	v_mov_b32_e32 v115, v0
	v_mov_b32_e32 v116, v0
	v_mov_b32_e32 v117, v0
	v_mov_b32_e32 v118, v0
	v_mov_b32_e32 v119, v0
	v_mov_b32_e32 v72, v0
	v_mov_b32_e32 v73, v0
	v_mov_b32_e32 v74, v0
	v_mov_b32_e32 v75, v0
	v_mov_b32_e32 v76, v0
	v_mov_b32_e32 v77, v0
	v_mov_b32_e32 v78, v0
	v_mov_b32_e32 v79, v0
	v_mov_b32_e32 v88, v0
	v_mov_b32_e32 v89, v0
	v_mov_b32_e32 v90, v0
	v_mov_b32_e32 v91, v0
	v_mov_b32_e32 v92, v0
	v_mov_b32_e32 v93, v0
	v_mov_b32_e32 v94, v0
	v_mov_b32_e32 v95, v0
	v_mov_b32_e32 v104, v0
	v_mov_b32_e32 v105, v0
	v_mov_b32_e32 v106, v0
	v_mov_b32_e32 v107, v0
	v_mov_b32_e32 v108, v0
	v_mov_b32_e32 v109, v0
	v_mov_b32_e32 v110, v0
	v_mov_b32_e32 v111, v0
	v_mov_b32_e32 v120, v0
	v_mov_b32_e32 v121, v0
	v_mov_b32_e32 v122, v0
	v_mov_b32_e32 v123, v0
	v_mov_b32_e32 v124, v0
	v_mov_b32_e32 v125, v0
	v_mov_b32_e32 v126, v0
	v_mov_b32_e32 v127, v0
	s_lshl_b32 s98, s4, 8
	s_add_i32 s98, s98, s51
	v_and_or_b32 v236, v222, 15, s98
	v_lshlrev_b32_e32 v236, 2, v236
	global_load_dword v228, v236, s[18:19]
	global_load_dword v229, v236, s[18:19] offset:64
	global_load_dword v230, v236, s[18:19] offset:128
	global_load_dword v231, v236, s[18:19] offset:192
	global_load_dword v232, v236, s[18:19] offset:512
	global_load_dword v233, v236, s[18:19] offset:576
	global_load_dword v234, v236, s[18:19] offset:640
	global_load_dword v235, v236, s[18:19] offset:704

; __device__ __forceinline__ unsigned cvt_pk_bf16(float lo, float hi) { unsigned r; asm volatile("v_cvt_pk_bf16_f32 %0, %1, %2" : "=v"(r) : "v"(lo), "v"(hi)); return r; }
;     __device__ __forceinline__ void operator()(const f32x4 (&acc)[2][2][4][2], const Unit& u, int wr, int wc, int fr_, int fq_) const {
;     ...
;         const int col0 = u.pn * BM + wc * 32 + 8 * fq, rowb = u.pm * BM + wr * 64 + fr;
;         float rs[2][4];
; #pragma unroll
;         for (int ai = 0; ai < 2; ++ai)
; #pragma unroll
;             for (int m = 0; m < 4; ++m) rs[ai][m] = rstd[rowb + ai * HALF + m * 16];
; #pragma unroll
;         for (int ai = 0; ai < 2; ++ai)
; #pragma unroll
;             for (int m = 0; m < 4; ++m) { const int row = rowb + ai * HALF + m * 16; const float r1 = rs[ai][m];
;                 bf16_t* rowp = O + (size_t)row * ldc + col0;
; #pragma unroll
;                 for (int bj = 0; bj < 2; ++bj) { f32x4 v0 = acc[ai][bj][m][0] * r1, v1 = acc[ai][bj][m][1] * r1;
;                     if (act == 1) { v0 = __builtin_elementwise_max(v0, (f32x4){0.f, 0.f, 0.f, 0.f}); v1 = __builtin_elementwise_max(v1, (f32x4){0.f, 0.f, 0.f, 0.f}); v0 = v0 * v0; v1 = v1 * v1; }
;                     v0 = v0 * scale; v1 = v1 * scale;
;                     u32x4 w; w.x = cvt_pk_bf16(v0[0], v0[1]); w.y = cvt_pk_bf16(v0[2], v0[3]); w.z = cvt_pk_bf16(v1[0], v1[1]); w.w = cvt_pk_bf16(v1[2], v1[3]);
;                     *(u32x4*)(rowp + bj * HALF) = w; } }
.LBB0_2038:
	s_lshl_b32 s4, s4, 8
	v_mov_b32_e32 v139, v222
	s_add_i32 s4, s4, s51
	s_andn2_b64 vcc, exec, s[16:17]
	v_and_or_b32 v140, v139, 15, s4
	v_or_b32_e32 v158, 16, v140
	v_or_b32_e32 v154, 32, v140
	v_or_b32_e32 v150, 48, v140
	v_ashrrev_i32_e32 v141, 31, v140
	v_ashrrev_i32_e32 v159, 31, v158
	v_ashrrev_i32_e32 v155, 31, v154
	v_ashrrev_i32_e32 v151, 31, v150
	v_lshl_add_u64 v[162:163], v[140:141], 2, s[18:19]
	v_lshl_add_u64 v[142:143], v[158:159], 2, s[18:19]
	v_lshl_add_u64 v[144:145], v[154:155], 2, s[18:19]
	v_lshl_add_u64 v[146:147], v[150:151], 2, s[18:19]
	s_waitcnt vmcnt(0)
	v_mov_b32_e32 v160, v228
	v_mov_b32_e32 v156, v229
	v_mov_b32_e32 v152, v230
	v_mov_b32_e32 v148, v231
	s_nop 0
	v_mov_b32_e32 v146, v232
	v_mov_b32_e32 v144, v233
	v_mov_b32_e32 v142, v234
	v_mov_b32_e32 v138, v235
	v_cndmask_b32_e64 v143, 0, 1, s[16:17]
	v_cmp_ne_u32_e64 s[4:5], 1, v143
	v_pk_mul_f32 v[126:127], v[126:127], v[160:161] op_sel_hi:[1,0]
	v_pk_mul_f32 v[162:163], v[124:125], v[160:161] op_sel_hi:[1,0]
	v_pk_mul_f32 v[124:125], v[122:123], v[160:161] op_sel_hi:[1,0]
	v_pk_mul_f32 v[164:165], v[120:121], v[160:161] op_sel_hi:[1,0]
	s_cbranch_vccnz .LBB0_2040
	v_max_f32_e32 v122, 0, v126
	v_max_f32_e32 v120, 0, v162
	v_max_f32_e32 v123, 0, v127
	v_max_f32_e32 v121, 0, v163
	v_max_f32_e32 v165, 0, v165
	v_max_f32_e32 v125, 0, v125
	v_max_f32_e32 v124, 0, v124
	v_max_f32_e32 v164, 0, v164
	v_pk_mul_f32 v[126:127], v[122:123], v[122:123]
	v_pk_mul_f32 v[162:163], v[120:121], v[120:121]
	v_pk_mul_f32 v[124:125], v[124:125], v[124:125]
	v_pk_mul_f32 v[164:165], v[164:165], v[164:165]
